# P2 work queues: one parallel probe of all 8 queue counters when the own queue drains; provably empty queues are skipped (saves up to 7 serialized atomic pops per workgroup)
# speedup vs baseline: 1.0047x; 1.0013x over previous
.LBB0_433:
	s_add_i32 s51, s51, 1
	s_add_i32 s2, s80, 1
	s_cmp_lg_u32 s51, 1
	s_cbranch_scc1 .Lq_nocheck
	s_waitcnt lgkmcnt(0)
	s_barrier
	v_readfirstlane_b32 s99, v188
	s_cmp_lg_u32 s99, 0
	s_cbranch_scc1 .Lq_probed
	v_lshlrev_b32_e32 v250, 8, v188
	v_readlane_b32 s100, v249, 43
	v_readlane_b32 s101, v249, 44
	v_mov_b32_e32 v252, 0x23ff8
	s_nop 4
	global_load_dword v251, v250, s[100:101] sc1
	s_waitcnt vmcnt(0)
	v_cmp_gt_u32_e32 vcc, 0xc4, v251
	s_nop 1
	s_and_b32 s98, vcc_lo, 0xff
	v_mov_b32_e32 v250, s98
	ds_write_b32 v252, v250
.Lq_probed:
	s_waitcnt lgkmcnt(0)
	s_barrier
	v_mov_b32_e32 v252, 0x23ff8
	ds_read_b32 v250, v252
	s_waitcnt lgkmcnt(0)
	v_readfirstlane_b32 s98, v250
.Lq_nocheck:
	s_cmp_lg_u32 s51, 8
	s_cbranch_scc0 .LBB0_549
.LBB0_434:
	s_mov_b32 s80, s2
	s_and_b32 s4, s2, 7
	v_readlane_b32 s2, v249, 54
	s_add_i32 s2, s51, s2
	s_and_b32 s52, s2, 7
	s_cmp_eq_u32 s51, 0
	s_cbranch_scc1 .Lq_go
	s_lshr_b32 s99, s98, s52
	s_and_b32 s99, s99, 1
	s_cmp_eq_u32 s99, 0
	s_cbranch_scc1 .LBB0_433
.Lq_go:
	s_or_b32 s53, s52, 0xffffffc0
	s_lshl_b32 s2, s52, 8
	v_readlane_b32 s3, v249, 43
	s_add_u32 s84, s3, s2
	v_readlane_b32 s2, v249, 44
	s_addc_u32 s85, s2, 0
	s_or_b32 s54, s52, 0xfffffd00
	s_mov_b32 s81, s4
	s_or_b32 s55, s4, 0xfffffd00
	s_branch .LBB0_438

	.amdhsa_kernel _Z8mega_fwd6Paramsii
		.amdhsa_group_segment_fixed_size 0
		.amdhsa_private_segment_fixed_size 0
		.amdhsa_kernarg_size 472
		.amdhsa_user_sgpr_count 2
		.amdhsa_user_sgpr_dispatch_ptr 0
		.amdhsa_user_sgpr_queue_ptr 0
		.amdhsa_user_sgpr_kernarg_segment_ptr 1
		.amdhsa_user_sgpr_dispatch_id 0
		.amdhsa_user_sgpr_kernarg_preload_length 0
		.amdhsa_user_sgpr_kernarg_preload_offset 0
		.amdhsa_user_sgpr_private_segment_size 0
		.amdhsa_uses_dynamic_stack 0
		.amdhsa_enable_private_segment 0
		.amdhsa_system_sgpr_workgroup_id_x 1
		.amdhsa_system_sgpr_workgroup_id_y 0
		.amdhsa_system_sgpr_workgroup_id_z 0
		.amdhsa_system_sgpr_workgroup_info 0
		.amdhsa_system_vgpr_workitem_id 2
		.amdhsa_next_free_vgpr 256
		.amdhsa_next_free_sgpr 102
		.amdhsa_accum_offset 256
		.amdhsa_reserve_vcc 1
		.amdhsa_float_round_mode_32 0
		.amdhsa_float_round_mode_16_64 0
		.amdhsa_float_denorm_mode_32 3
		.amdhsa_float_denorm_mode_16_64 3
		.amdhsa_dx10_clamp 1
		.amdhsa_ieee_mode 1
		.amdhsa_fp16_overflow 0
		.amdhsa_tg_split 0
		.amdhsa_exception_fp_ieee_invalid_op 0
		.amdhsa_exception_fp_denorm_src 0
		.amdhsa_exception_fp_ieee_div_zero 0
		.amdhsa_exception_fp_ieee_overflow 0
		.amdhsa_exception_fp_ieee_underflow 0
		.amdhsa_exception_fp_ieee_inexact 0
		.amdhsa_exception_int_div_zero 0
	.end_amdhsa_kernel

amdhsa.kernels:
  - .agpr_count:     0
    .args:
      - .offset:         0
        .size:           208
        .value_kind:     by_value
      - .offset:         208
        .size:           4
        .value_kind:     by_value
      - .offset:         212
        .size:           4
        .value_kind:     by_value
      - .offset:         216
        .size:           4
        .value_kind:     hidden_block_count_x
      - .offset:         220
        .size:           4
        .value_kind:     hidden_block_count_y
      - .offset:         224
        .size:           4
        .value_kind:     hidden_block_count_z
      - .offset:         228
        .size:           2
        .value_kind:     hidden_group_size_x
      - .offset:         230
        .size:           2
        .value_kind:     hidden_group_size_y
      - .offset:         232
        .size:           2
        .value_kind:     hidden_group_size_z
      - .offset:         234
        .size:           2
        .value_kind:     hidden_remainder_x
      - .offset:         236
        .size:           2
        .value_kind:     hidden_remainder_y
      - .offset:         238
        .size:           2
        .value_kind:     hidden_remainder_z
      - .offset:         256
        .size:           8
        .value_kind:     hidden_global_offset_x
      - .offset:         264
        .size:           8
        .value_kind:     hidden_global_offset_y
      - .offset:         272
        .size:           8
        .value_kind:     hidden_global_offset_z
      - .offset:         280
        .size:           2
        .value_kind:     hidden_grid_dims
      - .offset:         304
        .size:           8
        .value_kind:     hidden_multigrid_sync_arg
      - .offset:         336
        .size:           4
        .value_kind:     hidden_dynamic_lds_size
    .group_segment_fixed_size: 0
    .kernarg_segment_align: 8
    .kernarg_segment_size: 472
    .language:       OpenCL C
    .language_version:
      - 2
      - 0
    .max_flat_workgroup_size: 512
    .name:           _Z8mega_fwd6Paramsii
    .private_segment_fixed_size: 0
    .sgpr_count:     108
    .sgpr_spill_count: 72
    .symbol:         _Z8mega_fwd6Paramsii.kd
    .uniform_work_group_size: 1
    .uses_dynamic_stack: false
    .vgpr_count:     256
    .vgpr_spill_count: 0
    .wavefront_size: 64
